# c15 + nt on the once-read f32 weight loads of the conversion phases
# speedup vs baseline: 1.0024x; 1.0024x over previous
; template <int KT, class F> DEVI void cvt_tile(F colptr, int ldsrc, int k0, bf16_t* out, int ldo, int v0, float* tile, int wv) {
;     ...
;     { const int vc = tid & 63, kk = tid >> 6; const float* cp = colptr(v0 + vc) + (size_t)k0 * ldsrc; float v[8 * KT];
; #pragma unroll
;       for (int r = 0; r < 8 * KT; ++r) v[r] = cp[(size_t)(r * 8 + kk) * ldsrc];
; #pragma unroll
;       for (int r = 0; r < 8 * KT; ++r) tile[vc * PITCH + r * 8 + kk] = v[r]; }
;     __syncthreads();
; DEVI void cvt_ffn_phase(const float* wg, const float* wu, const float* wd, unsigned char* ws, char* lds, int j0, int jstride, int wv) {
;     ...
;         if (job < 352) { const int vt = job >> 2, kg = job & 3; cvt_tile<4>(ColGU{wg, (long)((const char*)wu - (const char*)wg)}, DFF, kg * 256, Wgu, DM, vt * 64, tile, wv); }
.LBB0_94:
	s_andn2_b64 vcc, exec, s[6:7]
	s_cbranch_vccnz .LBB0_91
	s_and_b32 s7, s23, 0x300
	s_and_b32 s6, s25, 0xffffffc0
	s_bitcmp1_b32 s8, 3
	s_cselect_b32 s76, s13, 0
	s_cselect_b32 s46, s22, 0
	s_add_u32 s78, s9, s76
	s_addc_u32 s46, s10, s46
	s_and_b32 s76, s60, 0xffffff80
	v_mov_b32_e32 v6, v217
	s_ashr_i32 s77, s76, 31
	s_lshl_b64 s[76:77], s[76:77], 2
	v_and_b32_e32 v7, 63, v6
	s_add_u32 s76, s78, s76
	v_and_or_b32 v0, s25, 64, v7
	s_addc_u32 s77, s46, s77
	v_lshlrev_b32_e32 v0, 2, v0
	v_lshl_add_u64 v[2:3], s[76:77], 0, v[0:1]
	s_mul_i32 s46, s7, 0x2c00
	v_ashrrev_i32_e32 v8, 6, v6
	v_lshl_add_u64 v[2:3], v[2:3], 0, s[46:47]
	v_mad_i64_i32 v[4:5], s[76:77], v8, s44, v[2:3]
	global_load_dword v0, v[4:5], off nt
	v_add_u32_e32 v4, 8, v8
	v_mad_i64_i32 v[4:5], s[76:77], v4, s44, v[2:3]
	global_load_dword v9, v[4:5], off nt
	v_add_u32_e32 v4, 16, v8
	v_mad_i64_i32 v[4:5], s[76:77], v4, s44, v[2:3]
	global_load_dword v10, v[4:5], off nt
	v_add_u32_e32 v4, 24, v8
	v_mad_i64_i32 v[4:5], s[76:77], v4, s44, v[2:3]
	global_load_dword v11, v[4:5], off nt
	v_add_u32_e32 v4, 32, v8
	v_mad_i64_i32 v[4:5], s[76:77], v4, s44, v[2:3]
	global_load_dword v12, v[4:5], off nt
	v_add_u32_e32 v4, 40, v8
	v_mad_i64_i32 v[4:5], s[76:77], v4, s44, v[2:3]
	global_load_dword v13, v[4:5], off nt
	v_add_u32_e32 v4, 48, v8
	v_mad_i64_i32 v[4:5], s[76:77], v4, s44, v[2:3]
	global_load_dword v14, v[4:5], off nt
	v_add_u32_e32 v4, 56, v8
	v_mad_i64_i32 v[4:5], s[76:77], v4, s44, v[2:3]
	global_load_dword v15, v[4:5], off nt
	v_add_u32_e32 v4, 64, v8
	v_mad_i64_i32 v[4:5], s[76:77], v4, s44, v[2:3]
	global_load_dword v16, v[4:5], off nt
	v_add_u32_e32 v4, 0x48, v8
	v_mad_i64_i32 v[4:5], s[76:77], v4, s44, v[2:3]
	global_load_dword v17, v[4:5], off nt
	v_add_u32_e32 v4, 0x50, v8
	v_mad_i64_i32 v[4:5], s[76:77], v4, s44, v[2:3]
	global_load_dword v18, v[4:5], off nt
	v_add_u32_e32 v4, 0x58, v8
	v_mad_i64_i32 v[4:5], s[76:77], v4, s44, v[2:3]
	global_load_dword v19, v[4:5], off nt
	v_add_u32_e32 v4, 0x60, v8
	v_mad_i64_i32 v[4:5], s[76:77], v4, s44, v[2:3]
	global_load_dword v20, v[4:5], off nt
	v_add_u32_e32 v4, 0x68, v8
	v_mad_i64_i32 v[4:5], s[76:77], v4, s44, v[2:3]
	global_load_dword v21, v[4:5], off nt
	v_add_u32_e32 v4, 0x70, v8
	v_mad_i64_i32 v[4:5], s[76:77], v4, s44, v[2:3]
	global_load_dword v22, v[4:5], off nt
	v_add_u32_e32 v4, 0x78, v8
	v_mad_i64_i32 v[4:5], s[76:77], v4, s44, v[2:3]
	global_load_dword v23, v[4:5], off nt
	v_add_u32_e32 v4, 0x80, v8
	v_mad_i64_i32 v[4:5], s[76:77], v4, s44, v[2:3]
	global_load_dword v24, v[4:5], off nt
	v_add_u32_e32 v4, 0x88, v8
	v_mad_i64_i32 v[4:5], s[76:77], v4, s44, v[2:3]
	global_load_dword v25, v[4:5], off nt
	v_add_u32_e32 v4, 0x90, v8
	v_mad_i64_i32 v[4:5], s[76:77], v4, s44, v[2:3]
	global_load_dword v26, v[4:5], off nt
	v_add_u32_e32 v4, 0x98, v8
	v_mad_i64_i32 v[4:5], s[76:77], v4, s44, v[2:3]
	global_load_dword v27, v[4:5], off nt
	v_add_u32_e32 v4, 0xa0, v8
	v_mad_i64_i32 v[4:5], s[76:77], v4, s44, v[2:3]
	global_load_dword v28, v[4:5], off nt
	v_add_u32_e32 v4, 0xa8, v8
	v_mad_i64_i32 v[4:5], s[76:77], v4, s44, v[2:3]
	global_load_dword v29, v[4:5], off nt
	v_add_u32_e32 v4, 0xb0, v8
	v_mad_i64_i32 v[4:5], s[76:77], v4, s44, v[2:3]
	global_load_dword v30, v[4:5], off nt
	v_add_u32_e32 v4, 0xb8, v8
	v_mad_i64_i32 v[4:5], s[76:77], v4, s44, v[2:3]
	global_load_dword v31, v[4:5], off nt
	v_add_u32_e32 v4, 0xc0, v8
	v_mad_i64_i32 v[4:5], s[76:77], v4, s44, v[2:3]
	global_load_dword v32, v[4:5], off nt
	v_add_u32_e32 v4, 0xc8, v8
	v_mad_i64_i32 v[4:5], s[76:77], v4, s44, v[2:3]
	global_load_dword v33, v[4:5], off nt
	v_add_u32_e32 v4, 0xd0, v8
	v_mad_i64_i32 v[4:5], s[76:77], v4, s44, v[2:3]
	global_load_dword v34, v[4:5], off nt
	v_add_u32_e32 v4, 0xd8, v8
	v_mad_i64_i32 v[4:5], s[76:77], v4, s44, v[2:3]
	global_load_dword v35, v[4:5], off nt
	v_add_u32_e32 v4, 0xe0, v8
	v_mad_i64_i32 v[4:5], s[76:77], v4, s44, v[2:3]
	global_load_dword v36, v[4:5], off nt
	v_add_u32_e32 v4, 0xe8, v8
	v_mad_i64_i32 v[4:5], s[76:77], v4, s44, v[2:3]
	global_load_dword v37, v[4:5], off nt
	v_add_u32_e32 v4, 0xf0, v8
	v_mad_i64_i32 v[4:5], s[76:77], v4, s44, v[2:3]
	global_load_dword v4, v[4:5], off nt
	v_add_u32_e32 v5, 0xf8, v8
	v_mad_i64_i32 v[2:3], s[76:77], v5, s44, v[2:3]
	global_load_dword v2, v[2:3], off nt
	v_mul_u32_u24_e32 v3, 0x404, v7
	v_lshlrev_b32_e32 v5, 2, v8
	v_add3_u32 v3, 0, v3, v5
	v_add_u32_e32 v3, 0x8000, v3
	s_waitcnt vmcnt(0)
	ds_write2_b32 v3, v0, v9 offset1:8
	ds_write2_b32 v3, v10, v11 offset0:16 offset1:24
	ds_write2_b32 v3, v12, v13 offset0:32 offset1:40
	ds_write2_b32 v3, v14, v15 offset0:48 offset1:56
	ds_write2_b32 v3, v16, v17 offset0:64 offset1:72
	ds_write2_b32 v3, v18, v19 offset0:80 offset1:88
	ds_write2_b32 v3, v20, v21 offset0:96 offset1:104
	ds_write2_b32 v3, v22, v23 offset0:112 offset1:120
	ds_write2_b32 v3, v24, v25 offset0:128 offset1:136
	ds_write2_b32 v3, v26, v27 offset0:144 offset1:152
	ds_write2_b32 v3, v28, v29 offset0:160 offset1:168
	ds_write2_b32 v3, v30, v31 offset0:176 offset1:184
	ds_write2_b32 v3, v32, v33 offset0:192 offset1:200
	ds_write2_b32 v3, v34, v35 offset0:208 offset1:216
	ds_write2_b32 v3, v36, v37 offset0:224 offset1:232
	ds_write2_b32 v3, v4, v2 offset0:240 offset1:248
	v_lshlrev_b32_e32 v2, 3, v6
	v_ashrrev_i32_e32 v0, 3, v6
	v_and_b32_e32 v4, 56, v2
	v_mul_lo_u32 v2, v0, s43
	v_lshlrev_b32_e32 v3, 2, v4
	v_add3_u32 v10, 0, v2, v3
	s_lshl_b32 s7, s7, 1
	v_add_u32_e32 v2, s6, v0
	s_add_u32 s76, s72, s7
	v_ashrrev_i32_e32 v3, 31, v2
	s_addc_u32 s77, s73, 0
	v_lshlrev_b64 v[2:3], 11, v[2:3]
	v_add_u32_e32 v5, 0x8000, v10
	v_lshl_add_u64 v[2:3], s[76:77], 0, v[2:3]
	v_lshlrev_b32_e32 v0, 1, v4
	s_waitcnt lgkmcnt(0)
	s_barrier
; DEVI unsigned cvtpk(float lo, float hi) { unsigned r; asm volatile("v_cvt_pk_bf16_f32 %0, %1, %2" : "=v"(r) : "v"(lo), "v"(hi)); return r; }
; template <int KT, class F> DEVI void cvt_tile(F colptr, int ldsrc, int k0, bf16_t* out, int ldo, int v0, float* tile, int wv) {
;     ...
;     { const int vc = tid >> 3, k8 = (tid & 7) * 8;
; #pragma unroll
;       for (int q = 0; q < KT; ++q) { const float* tp = tile + vc * PITCH + q * 64 + k8;
;         u32x4 w = {cvtpk(tp[0], tp[1]), cvtpk(tp[2], tp[3]), cvtpk(tp[4], tp[5]), cvtpk(tp[6], tp[7])};
;         *(u32x4*)(out + (size_t)(v0 + vc) * ldo + k0 + q * 64 + k8) = w; } }
;     __syncthreads();
	v_lshl_add_u64 v[6:7], v[2:3], 0, v[0:1]
	ds_read2_b32 v[2:3], v5 offset1:1
	v_add_u32_e32 v0, 0x8008, v10
	s_waitcnt lgkmcnt(0)
	v_cvt_pk_bf16_f32 v2, v2, v3
	ds_read2_b32 v[4:5], v0 offset1:1
	v_add_u32_e32 v0, 0x8010, v10
	s_waitcnt lgkmcnt(0)
	v_cvt_pk_bf16_f32 v3, v4, v5
	ds_read2_b32 v[4:5], v0 offset1:1
	v_add_u32_e32 v0, 0x8018, v10
	s_waitcnt lgkmcnt(0)
	v_cvt_pk_bf16_f32 v4, v4, v5
	ds_read2_b32 v[8:9], v0 offset1:1
	s_waitcnt lgkmcnt(0)
	v_cvt_pk_bf16_f32 v5, v8, v9
	flat_store_dwordx4 v[6:7], v[2:5]
	v_add_u32_e32 v0, 0x8100, v10
	ds_read2_b32 v[2:3], v0 offset1:1
	v_add_u32_e32 v0, 0x8108, v10
	s_waitcnt lgkmcnt(0)
	v_cvt_pk_bf16_f32 v2, v2, v3
	ds_read2_b32 v[4:5], v0 offset1:1
	v_add_u32_e32 v0, 0x8110, v10
	s_waitcnt lgkmcnt(0)
	v_cvt_pk_bf16_f32 v3, v4, v5
	ds_read2_b32 v[4:5], v0 offset1:1
	v_add_u32_e32 v0, 0x8118, v10
	s_waitcnt lgkmcnt(0)
	v_cvt_pk_bf16_f32 v4, v4, v5
	ds_read2_b32 v[8:9], v0 offset1:1
	s_waitcnt lgkmcnt(0)
	v_cvt_pk_bf16_f32 v5, v8, v9
	flat_store_dwordx4 v[6:7], v[2:5] offset:128
	v_add_u32_e32 v0, 0x8200, v10
	ds_read2_b32 v[2:3], v0 offset1:1
	v_add_u32_e32 v0, 0x8208, v10
	s_waitcnt lgkmcnt(0)
	v_cvt_pk_bf16_f32 v2, v2, v3
	ds_read2_b32 v[4:5], v0 offset1:1
	v_add_u32_e32 v0, 0x8210, v10
	s_waitcnt lgkmcnt(0)
	v_cvt_pk_bf16_f32 v3, v4, v5
	ds_read2_b32 v[4:5], v0 offset1:1
	v_add_u32_e32 v0, 0x8218, v10
	s_waitcnt lgkmcnt(0)
	v_cvt_pk_bf16_f32 v4, v4, v5
	ds_read2_b32 v[8:9], v0 offset1:1
	s_waitcnt lgkmcnt(0)
	v_cvt_pk_bf16_f32 v5, v8, v9
	flat_store_dwordx4 v[6:7], v[2:5] offset:256
	v_add_u32_e32 v0, 0x8300, v10
	ds_read2_b32 v[2:3], v0 offset1:1
	v_add_u32_e32 v0, 0x8308, v10
	s_waitcnt lgkmcnt(0)
	v_cvt_pk_bf16_f32 v2, v2, v3
	ds_read2_b32 v[4:5], v0 offset1:1
	v_add_u32_e32 v0, 0x8310, v10
	s_waitcnt lgkmcnt(0)
	v_cvt_pk_bf16_f32 v3, v4, v5
	ds_read2_b32 v[4:5], v0 offset1:1
	v_add_u32_e32 v0, 0x8318, v10
	s_waitcnt lgkmcnt(0)
	v_cvt_pk_bf16_f32 v4, v4, v5
	ds_read2_b32 v[8:9], v0 offset1:1
	s_waitcnt lgkmcnt(0)
	v_cvt_pk_bf16_f32 v5, v8, v9
	flat_store_dwordx4 v[6:7], v[2:5] offset:384
	s_waitcnt lgkmcnt(0)
	s_barrier
	s_branch .LBB0_91

; template <int KT, class F> DEVI void cvt_tile(F colptr, int ldsrc, int k0, bf16_t* out, int ldo, int v0, float* tile, int wv) {
;     ...
;     { const int vc = tid & 63, kk = tid >> 6; const float* cp = colptr(v0 + vc) + (size_t)k0 * ldsrc; float v[8 * KT];
; #pragma unroll
;       for (int r = 0; r < 8 * KT; ++r) v[r] = cp[(size_t)(r * 8 + kk) * ldsrc];
; #pragma unroll
;       for (int r = 0; r < 8 * KT; ++r) tile[vc * PITCH + r * 8 + kk] = v[r]; }
;     __syncthreads();
; DEVI void cvt_ffn_phase(const float* wg, const float* wu, const float* wd, unsigned char* ws, char* lds, int j0, int jstride, int wv) {
;     ...
;         if (job < 352) { const int vt = job >> 2, kg = job & 3; cvt_tile<4>(ColGU{wg, (long)((const char*)wu - (const char*)wg)}, DFF, kg * 256, Wgu, DM, vt * 64, tile, wv); }
.LBB0_102:
	s_andn2_b64 vcc, exec, s[6:7]
	s_cbranch_vccnz .LBB0_99
	s_and_b32 s7, s13, 0x300
	s_and_b32 s6, s23, 0xffffffc0
	s_bitcmp1_b32 s60, 3
	s_cselect_b32 s61, s10, 0
	s_cselect_b32 s46, s11, 0
	s_add_u32 s61, s8, s61
	s_addc_u32 s46, s9, s46
	s_and_b32 s76, s25, 0xffffff80
	v_mov_b32_e32 v6, v217
	s_ashr_i32 s77, s76, 31
	s_lshl_b64 s[76:77], s[76:77], 2
	v_and_b32_e32 v7, 63, v6
	s_add_u32 s76, s61, s76
	v_and_or_b32 v0, s23, 64, v7
	s_addc_u32 s77, s46, s77
	v_lshlrev_b32_e32 v0, 2, v0
	v_lshl_add_u64 v[2:3], s[76:77], 0, v[0:1]
	s_mul_i32 s46, s7, 0x2c00
	v_ashrrev_i32_e32 v8, 6, v6
	v_lshl_add_u64 v[2:3], v[2:3], 0, s[46:47]
	v_mad_i64_i32 v[4:5], s[76:77], v8, s44, v[2:3]
	global_load_dword v0, v[4:5], off nt
	v_add_u32_e32 v4, 8, v8
	v_mad_i64_i32 v[4:5], s[76:77], v4, s44, v[2:3]
	global_load_dword v9, v[4:5], off nt
	v_add_u32_e32 v4, 16, v8
	v_mad_i64_i32 v[4:5], s[76:77], v4, s44, v[2:3]
	global_load_dword v10, v[4:5], off nt
	v_add_u32_e32 v4, 24, v8
	v_mad_i64_i32 v[4:5], s[76:77], v4, s44, v[2:3]
	global_load_dword v11, v[4:5], off nt
	v_add_u32_e32 v4, 32, v8
	v_mad_i64_i32 v[4:5], s[76:77], v4, s44, v[2:3]
	global_load_dword v12, v[4:5], off nt
	v_add_u32_e32 v4, 40, v8
	v_mad_i64_i32 v[4:5], s[76:77], v4, s44, v[2:3]
	global_load_dword v13, v[4:5], off nt
	v_add_u32_e32 v4, 48, v8
	v_mad_i64_i32 v[4:5], s[76:77], v4, s44, v[2:3]
	global_load_dword v14, v[4:5], off nt
	v_add_u32_e32 v4, 56, v8
	v_mad_i64_i32 v[4:5], s[76:77], v4, s44, v[2:3]
	global_load_dword v15, v[4:5], off nt
	v_add_u32_e32 v4, 64, v8
	v_mad_i64_i32 v[4:5], s[76:77], v4, s44, v[2:3]
	global_load_dword v16, v[4:5], off nt
	v_add_u32_e32 v4, 0x48, v8
	v_mad_i64_i32 v[4:5], s[76:77], v4, s44, v[2:3]
	global_load_dword v17, v[4:5], off nt
	v_add_u32_e32 v4, 0x50, v8
	v_mad_i64_i32 v[4:5], s[76:77], v4, s44, v[2:3]
	global_load_dword v18, v[4:5], off nt
	v_add_u32_e32 v4, 0x58, v8
	v_mad_i64_i32 v[4:5], s[76:77], v4, s44, v[2:3]
	global_load_dword v19, v[4:5], off nt
	v_add_u32_e32 v4, 0x60, v8
	v_mad_i64_i32 v[4:5], s[76:77], v4, s44, v[2:3]
	global_load_dword v20, v[4:5], off nt
	v_add_u32_e32 v4, 0x68, v8
	v_mad_i64_i32 v[4:5], s[76:77], v4, s44, v[2:3]
	global_load_dword v21, v[4:5], off nt
	v_add_u32_e32 v4, 0x70, v8
	v_mad_i64_i32 v[4:5], s[76:77], v4, s44, v[2:3]
	global_load_dword v22, v[4:5], off nt
	v_add_u32_e32 v4, 0x78, v8
	v_mad_i64_i32 v[4:5], s[76:77], v4, s44, v[2:3]
	global_load_dword v23, v[4:5], off nt
	v_add_u32_e32 v4, 0x80, v8
	v_mad_i64_i32 v[4:5], s[76:77], v4, s44, v[2:3]
	global_load_dword v24, v[4:5], off nt
	v_add_u32_e32 v4, 0x88, v8
	v_mad_i64_i32 v[4:5], s[76:77], v4, s44, v[2:3]
	global_load_dword v25, v[4:5], off nt
	v_add_u32_e32 v4, 0x90, v8
	v_mad_i64_i32 v[4:5], s[76:77], v4, s44, v[2:3]
	global_load_dword v26, v[4:5], off nt
	v_add_u32_e32 v4, 0x98, v8
	v_mad_i64_i32 v[4:5], s[76:77], v4, s44, v[2:3]
	global_load_dword v27, v[4:5], off nt
	v_add_u32_e32 v4, 0xa0, v8
	v_mad_i64_i32 v[4:5], s[76:77], v4, s44, v[2:3]
	global_load_dword v28, v[4:5], off nt
	v_add_u32_e32 v4, 0xa8, v8
	v_mad_i64_i32 v[4:5], s[76:77], v4, s44, v[2:3]
	global_load_dword v29, v[4:5], off nt
	v_add_u32_e32 v4, 0xb0, v8
	v_mad_i64_i32 v[4:5], s[76:77], v4, s44, v[2:3]
	global_load_dword v30, v[4:5], off nt
	v_add_u32_e32 v4, 0xb8, v8
	v_mad_i64_i32 v[4:5], s[76:77], v4, s44, v[2:3]
	global_load_dword v31, v[4:5], off nt
	v_add_u32_e32 v4, 0xc0, v8
	v_mad_i64_i32 v[4:5], s[76:77], v4, s44, v[2:3]
	global_load_dword v32, v[4:5], off nt
	v_add_u32_e32 v4, 0xc8, v8
	v_mad_i64_i32 v[4:5], s[76:77], v4, s44, v[2:3]
	global_load_dword v33, v[4:5], off nt
	v_add_u32_e32 v4, 0xd0, v8
	v_mad_i64_i32 v[4:5], s[76:77], v4, s44, v[2:3]
	global_load_dword v34, v[4:5], off nt
	v_add_u32_e32 v4, 0xd8, v8
	v_mad_i64_i32 v[4:5], s[76:77], v4, s44, v[2:3]
	global_load_dword v35, v[4:5], off nt
	v_add_u32_e32 v4, 0xe0, v8
	v_mad_i64_i32 v[4:5], s[76:77], v4, s44, v[2:3]
	global_load_dword v36, v[4:5], off nt
	v_add_u32_e32 v4, 0xe8, v8
	v_mad_i64_i32 v[4:5], s[76:77], v4, s44, v[2:3]
	global_load_dword v37, v[4:5], off nt
	v_add_u32_e32 v4, 0xf0, v8
	v_mad_i64_i32 v[4:5], s[76:77], v4, s44, v[2:3]
	global_load_dword v4, v[4:5], off nt
	v_add_u32_e32 v5, 0xf8, v8
	v_mad_i64_i32 v[2:3], s[76:77], v5, s44, v[2:3]
	global_load_dword v2, v[2:3], off nt
	v_mul_u32_u24_e32 v3, 0x404, v7
	v_lshlrev_b32_e32 v5, 2, v8
	v_add3_u32 v3, 0, v3, v5
	v_add_u32_e32 v3, 0x8000, v3
	s_waitcnt vmcnt(0)
	ds_write2_b32 v3, v0, v9 offset1:8
	ds_write2_b32 v3, v10, v11 offset0:16 offset1:24
	ds_write2_b32 v3, v12, v13 offset0:32 offset1:40
	ds_write2_b32 v3, v14, v15 offset0:48 offset1:56
	ds_write2_b32 v3, v16, v17 offset0:64 offset1:72
	ds_write2_b32 v3, v18, v19 offset0:80 offset1:88
	ds_write2_b32 v3, v20, v21 offset0:96 offset1:104
	ds_write2_b32 v3, v22, v23 offset0:112 offset1:120
	ds_write2_b32 v3, v24, v25 offset0:128 offset1:136
	ds_write2_b32 v3, v26, v27 offset0:144 offset1:152
	ds_write2_b32 v3, v28, v29 offset0:160 offset1:168
	ds_write2_b32 v3, v30, v31 offset0:176 offset1:184
	ds_write2_b32 v3, v32, v33 offset0:192 offset1:200
	ds_write2_b32 v3, v34, v35 offset0:208 offset1:216
	ds_write2_b32 v3, v36, v37 offset0:224 offset1:232
	ds_write2_b32 v3, v4, v2 offset0:240 offset1:248
	v_lshlrev_b32_e32 v2, 3, v6
	v_ashrrev_i32_e32 v0, 3, v6
	v_and_b32_e32 v4, 56, v2
	v_mul_lo_u32 v2, v0, s43
	v_lshlrev_b32_e32 v3, 2, v4
	v_add3_u32 v10, 0, v2, v3
	s_lshl_b32 s7, s7, 1
	v_add_u32_e32 v2, s6, v0
	s_add_u32 s76, s72, s7
	v_ashrrev_i32_e32 v3, 31, v2
	s_addc_u32 s77, s73, 0
	v_lshlrev_b64 v[2:3], 11, v[2:3]
	v_add_u32_e32 v5, 0x8000, v10
	v_lshl_add_u64 v[2:3], s[76:77], 0, v[2:3]
	v_lshlrev_b32_e32 v0, 1, v4
	s_waitcnt lgkmcnt(0)
	s_barrier
; DEVI unsigned cvtpk(float lo, float hi) { unsigned r; asm volatile("v_cvt_pk_bf16_f32 %0, %1, %2" : "=v"(r) : "v"(lo), "v"(hi)); return r; }
; template <int KT, class F> DEVI void cvt_tile(F colptr, int ldsrc, int k0, bf16_t* out, int ldo, int v0, float* tile, int wv) {
;     ...
;     { const int vc = tid >> 3, k8 = (tid & 7) * 8;
; #pragma unroll
;       for (int q = 0; q < KT; ++q) { const float* tp = tile + vc * PITCH + q * 64 + k8;
;         u32x4 w = {cvtpk(tp[0], tp[1]), cvtpk(tp[2], tp[3]), cvtpk(tp[4], tp[5]), cvtpk(tp[6], tp[7])};
;         *(u32x4*)(out + (size_t)(v0 + vc) * ldo + k0 + q * 64 + k8) = w; } }
;     __syncthreads();
	v_lshl_add_u64 v[6:7], v[2:3], 0, v[0:1]
	ds_read2_b32 v[2:3], v5 offset1:1
	v_add_u32_e32 v0, 0x8008, v10
	s_waitcnt lgkmcnt(0)
	v_cvt_pk_bf16_f32 v2, v2, v3
	ds_read2_b32 v[4:5], v0 offset1:1
	v_add_u32_e32 v0, 0x8010, v10
	s_waitcnt lgkmcnt(0)
	v_cvt_pk_bf16_f32 v3, v4, v5
	ds_read2_b32 v[4:5], v0 offset1:1
	v_add_u32_e32 v0, 0x8018, v10
	s_waitcnt lgkmcnt(0)
	v_cvt_pk_bf16_f32 v4, v4, v5
	ds_read2_b32 v[8:9], v0 offset1:1
	s_waitcnt lgkmcnt(0)
	v_cvt_pk_bf16_f32 v5, v8, v9
	flat_store_dwordx4 v[6:7], v[2:5]
	v_add_u32_e32 v0, 0x8100, v10
	ds_read2_b32 v[2:3], v0 offset1:1
	v_add_u32_e32 v0, 0x8108, v10
	s_waitcnt lgkmcnt(0)
	v_cvt_pk_bf16_f32 v2, v2, v3
	ds_read2_b32 v[4:5], v0 offset1:1
	v_add_u32_e32 v0, 0x8110, v10
	s_waitcnt lgkmcnt(0)
	v_cvt_pk_bf16_f32 v3, v4, v5
	ds_read2_b32 v[4:5], v0 offset1:1
	v_add_u32_e32 v0, 0x8118, v10
	s_waitcnt lgkmcnt(0)
	v_cvt_pk_bf16_f32 v4, v4, v5
	ds_read2_b32 v[8:9], v0 offset1:1
	s_waitcnt lgkmcnt(0)
	v_cvt_pk_bf16_f32 v5, v8, v9
	flat_store_dwordx4 v[6:7], v[2:5] offset:128
	v_add_u32_e32 v0, 0x8200, v10
	ds_read2_b32 v[2:3], v0 offset1:1
	v_add_u32_e32 v0, 0x8208, v10
	s_waitcnt lgkmcnt(0)
	v_cvt_pk_bf16_f32 v2, v2, v3
	ds_read2_b32 v[4:5], v0 offset1:1
	v_add_u32_e32 v0, 0x8210, v10
	s_waitcnt lgkmcnt(0)
	v_cvt_pk_bf16_f32 v3, v4, v5
	ds_read2_b32 v[4:5], v0 offset1:1
	v_add_u32_e32 v0, 0x8218, v10
	s_waitcnt lgkmcnt(0)
	v_cvt_pk_bf16_f32 v4, v4, v5
	ds_read2_b32 v[8:9], v0 offset1:1
	s_waitcnt lgkmcnt(0)
	v_cvt_pk_bf16_f32 v5, v8, v9
	flat_store_dwordx4 v[6:7], v[2:5] offset:256
	v_add_u32_e32 v0, 0x8300, v10
	ds_read2_b32 v[2:3], v0 offset1:1
	v_add_u32_e32 v0, 0x8308, v10
	s_waitcnt lgkmcnt(0)
	v_cvt_pk_bf16_f32 v2, v2, v3
	ds_read2_b32 v[4:5], v0 offset1:1
	v_add_u32_e32 v0, 0x8310, v10
	s_waitcnt lgkmcnt(0)
	v_cvt_pk_bf16_f32 v3, v4, v5
	ds_read2_b32 v[4:5], v0 offset1:1
	v_add_u32_e32 v0, 0x8318, v10
	s_waitcnt lgkmcnt(0)
	v_cvt_pk_bf16_f32 v4, v4, v5
	ds_read2_b32 v[8:9], v0 offset1:1
	s_waitcnt lgkmcnt(0)
	v_cvt_pk_bf16_f32 v5, v8, v9
	flat_store_dwordx4 v[6:7], v[2:5] offset:384
	s_waitcnt lgkmcnt(0)
	s_barrier
	s_branch .LBB0_99

; template <int KT, class F> DEVI void cvt_tile(F colptr, int ldsrc, int k0, bf16_t* out, int ldo, int v0, float* tile, int wv) {
;     ...
;     { const int vc = tid & 63, kk = tid >> 6; const float* cp = colptr(v0 + vc) + (size_t)k0 * ldsrc; float v[8 * KT];
; #pragma unroll
;       for (int r = 0; r < 8 * KT; ++r) v[r] = cp[(size_t)(r * 8 + kk) * ldsrc];
; #pragma unroll
;       for (int r = 0; r < 8 * KT; ++r) tile[vc * PITCH + r * 8 + kk] = v[r]; }
;     __syncthreads();
; DEVI void cvt_mix_phase(const float* win, const float* woa, const float* wor, const float* wout, const float* lwa, const float* lwx, unsigned char* ws, char* lds, int wv) {
;     ...
;         if (job < 448) { const int vt = job >> 2, kg = job & 3; cvt_tile<4>(ColIn{win}, NIN, kg * 256, (bf16_t*)(ws + WS_WIN), DM, vt * 64, tile, wv); }
.LBB0_460:
	s_andn2_b64 vcc, exec, s[22:23]
	s_cbranch_vccnz .LBB0_450
	s_lshl_b32 s22, s59, 8
	s_lshl_b32 s24, s59, 4
	v_mov_b32_e32 v0, v217
	s_and_b32 s23, s22, 0x300
	s_and_b32 s22, s24, 0xffffffc0
	s_mul_i32 s46, s23, 0x7020
	v_bfi_b32 v2, 63, v0, s24
	s_movk_i32 s24, 0xc00
	v_cmp_gt_i32_e32 vcc, s24, v2
	v_add_u32_e32 v3, 8, v2
	v_ashrrev_i32_e32 v7, 6, v0
	v_cndmask_b32_e32 v2, v3, v2, vcc
	v_ashrrev_i32_e32 v3, 31, v2
	v_lshl_add_u64 v[2:3], v[2:3], 2, s[8:9]
	v_lshl_add_u64 v[2:3], v[2:3], 0, s[46:47]
	v_mad_i64_i32 v[4:5], s[24:25], v7, s52, v[2:3]
	global_load_dword v8, v[4:5], off nt
	v_add_u32_e32 v4, 8, v7
	v_mad_i64_i32 v[4:5], s[24:25], v4, s52, v[2:3]
	global_load_dword v9, v[4:5], off nt
	v_add_u32_e32 v4, 16, v7
	v_mad_i64_i32 v[4:5], s[24:25], v4, s52, v[2:3]
	global_load_dword v10, v[4:5], off nt
	v_add_u32_e32 v4, 24, v7
	v_mad_i64_i32 v[4:5], s[24:25], v4, s52, v[2:3]
	global_load_dword v11, v[4:5], off nt
	v_add_u32_e32 v4, 32, v7
	v_mad_i64_i32 v[4:5], s[24:25], v4, s52, v[2:3]
	global_load_dword v12, v[4:5], off nt
	v_add_u32_e32 v4, 40, v7
	v_mad_i64_i32 v[4:5], s[24:25], v4, s52, v[2:3]
	global_load_dword v13, v[4:5], off nt
	v_add_u32_e32 v4, 48, v7
	v_mad_i64_i32 v[4:5], s[24:25], v4, s52, v[2:3]
	global_load_dword v14, v[4:5], off nt
	v_add_u32_e32 v4, 56, v7
	v_mad_i64_i32 v[4:5], s[24:25], v4, s52, v[2:3]
	global_load_dword v15, v[4:5], off nt
	v_add_u32_e32 v4, 64, v7
	v_mad_i64_i32 v[4:5], s[24:25], v4, s52, v[2:3]
	global_load_dword v16, v[4:5], off nt
	v_add_u32_e32 v4, 0x48, v7
	v_mad_i64_i32 v[4:5], s[24:25], v4, s52, v[2:3]
	global_load_dword v17, v[4:5], off nt
	v_add_u32_e32 v4, 0x50, v7
	v_mad_i64_i32 v[4:5], s[24:25], v4, s52, v[2:3]
	global_load_dword v18, v[4:5], off nt
	v_add_u32_e32 v4, 0x58, v7
	v_mad_i64_i32 v[4:5], s[24:25], v4, s52, v[2:3]
	global_load_dword v19, v[4:5], off nt
	v_add_u32_e32 v4, 0x60, v7
	v_mad_i64_i32 v[4:5], s[24:25], v4, s52, v[2:3]
	global_load_dword v20, v[4:5], off nt
	v_add_u32_e32 v4, 0x68, v7
	v_mad_i64_i32 v[4:5], s[24:25], v4, s52, v[2:3]
	global_load_dword v21, v[4:5], off nt
	v_add_u32_e32 v4, 0x70, v7
	v_mad_i64_i32 v[4:5], s[24:25], v4, s52, v[2:3]
	global_load_dword v22, v[4:5], off nt
	v_add_u32_e32 v4, 0x78, v7
	v_mad_i64_i32 v[4:5], s[24:25], v4, s52, v[2:3]
	global_load_dword v23, v[4:5], off nt
	v_add_u32_e32 v4, 0x80, v7
	v_mad_i64_i32 v[4:5], s[24:25], v4, s52, v[2:3]
	global_load_dword v24, v[4:5], off nt
	v_add_u32_e32 v4, 0x88, v7
	v_mad_i64_i32 v[4:5], s[24:25], v4, s52, v[2:3]
	global_load_dword v25, v[4:5], off nt
	v_add_u32_e32 v4, 0x90, v7
	v_mad_i64_i32 v[4:5], s[24:25], v4, s52, v[2:3]
	global_load_dword v26, v[4:5], off nt
	v_add_u32_e32 v4, 0x98, v7
	v_mad_i64_i32 v[4:5], s[24:25], v4, s52, v[2:3]
	global_load_dword v27, v[4:5], off nt
	v_add_u32_e32 v4, 0xa0, v7
	v_mad_i64_i32 v[4:5], s[24:25], v4, s52, v[2:3]
	global_load_dword v28, v[4:5], off nt
	v_add_u32_e32 v4, 0xa8, v7
	v_mad_i64_i32 v[4:5], s[24:25], v4, s52, v[2:3]
	global_load_dword v29, v[4:5], off nt
	v_add_u32_e32 v4, 0xb0, v7
	v_mad_i64_i32 v[4:5], s[24:25], v4, s52, v[2:3]
	global_load_dword v30, v[4:5], off nt
	v_add_u32_e32 v4, 0xb8, v7
	v_mad_i64_i32 v[4:5], s[24:25], v4, s52, v[2:3]
	global_load_dword v31, v[4:5], off nt
	v_add_u32_e32 v4, 0xc0, v7
	v_mad_i64_i32 v[4:5], s[24:25], v4, s52, v[2:3]
	global_load_dword v32, v[4:5], off nt
	v_add_u32_e32 v4, 0xc8, v7
	v_mad_i64_i32 v[4:5], s[24:25], v4, s52, v[2:3]
	global_load_dword v33, v[4:5], off nt
	v_add_u32_e32 v4, 0xd0, v7
	v_mad_i64_i32 v[4:5], s[24:25], v4, s52, v[2:3]
	global_load_dword v34, v[4:5], off nt
	v_add_u32_e32 v4, 0xd8, v7
	v_mad_i64_i32 v[4:5], s[24:25], v4, s52, v[2:3]
	global_load_dword v35, v[4:5], off nt
	v_add_u32_e32 v4, 0xe0, v7
	v_mad_i64_i32 v[4:5], s[24:25], v4, s52, v[2:3]
	global_load_dword v36, v[4:5], off nt
	v_add_u32_e32 v4, 0xe8, v7
	v_mad_i64_i32 v[4:5], s[24:25], v4, s52, v[2:3]
	global_load_dword v37, v[4:5], off nt
	v_add_u32_e32 v4, 0xf0, v7
	v_mad_i64_i32 v[4:5], s[24:25], v4, s52, v[2:3]
	global_load_dword v4, v[4:5], off nt
	v_add_u32_e32 v5, 0xf8, v7
	v_mad_i64_i32 v[2:3], s[24:25], v5, s52, v[2:3]
	global_load_dword v2, v[2:3], off nt
	v_and_b32_e32 v6, 63, v0
	v_mul_u32_u24_e32 v3, 0x404, v6
	v_lshlrev_b32_e32 v5, 2, v7
	v_add3_u32 v3, 0, v3, v5
	v_add_u32_e32 v3, 0x8000, v3
	s_waitcnt vmcnt(0)
	ds_write2_b32 v3, v8, v9 offset1:8
	ds_write2_b32 v3, v10, v11 offset0:16 offset1:24
	ds_write2_b32 v3, v12, v13 offset0:32 offset1:40
	ds_write2_b32 v3, v14, v15 offset0:48 offset1:56
	ds_write2_b32 v3, v16, v17 offset0:64 offset1:72
	ds_write2_b32 v3, v18, v19 offset0:80 offset1:88
	ds_write2_b32 v3, v20, v21 offset0:96 offset1:104
	ds_write2_b32 v3, v22, v23 offset0:112 offset1:120
	ds_write2_b32 v3, v24, v25 offset0:128 offset1:136
	ds_write2_b32 v3, v26, v27 offset0:144 offset1:152
	ds_write2_b32 v3, v28, v29 offset0:160 offset1:168
	ds_write2_b32 v3, v30, v31 offset0:176 offset1:184
	ds_write2_b32 v3, v32, v33 offset0:192 offset1:200
	ds_write2_b32 v3, v34, v35 offset0:208 offset1:216
	ds_write2_b32 v3, v36, v37 offset0:224 offset1:232
	ds_write2_b32 v3, v4, v2 offset0:240 offset1:248
	v_ashrrev_i32_e32 v2, 3, v0
	v_lshlrev_b32_e32 v0, 3, v0
	v_and_b32_e32 v0, 56, v0
	v_mul_lo_u32 v3, v2, s43
	v_lshlrev_b32_e32 v4, 2, v0
	s_lshl_b32 s23, s23, 1
	v_add_u32_e32 v2, s22, v2
	v_add3_u32 v10, 0, v3, v4
	s_add_u32 s24, s91, s23
	v_ashrrev_i32_e32 v3, 31, v2
	s_addc_u32 s25, s92, 0
	v_lshlrev_b64 v[2:3], 11, v[2:3]
	v_add_u32_e32 v4, 0x8000, v10
	v_lshl_add_u64 v[2:3], s[24:25], 0, v[2:3]
	v_lshlrev_b32_e32 v0, 1, v0
	s_waitcnt lgkmcnt(0)
	s_barrier
; DEVI unsigned cvtpk(float lo, float hi) { unsigned r; asm volatile("v_cvt_pk_bf16_f32 %0, %1, %2" : "=v"(r) : "v"(lo), "v"(hi)); return r; }
; template <int KT, class F> DEVI void cvt_tile(F colptr, int ldsrc, int k0, bf16_t* out, int ldo, int v0, float* tile, int wv) {
;     ...
;     { const int vc = tid >> 3, k8 = (tid & 7) * 8;
; #pragma unroll
;       for (int q = 0; q < KT; ++q) { const float* tp = tile + vc * PITCH + q * 64 + k8;
;         u32x4 w = {cvtpk(tp[0], tp[1]), cvtpk(tp[2], tp[3]), cvtpk(tp[4], tp[5]), cvtpk(tp[6], tp[7])};
;         *(u32x4*)(out + (size_t)(v0 + vc) * ldo + k0 + q * 64 + k8) = w; } }
;     __syncthreads();
	v_lshl_add_u64 v[6:7], v[2:3], 0, v[0:1]
	ds_read2_b32 v[2:3], v4 offset1:1
	v_add_u32_e32 v0, 0x8008, v10
	s_waitcnt lgkmcnt(0)
	v_cvt_pk_bf16_f32 v2, v2, v3
	ds_read2_b32 v[4:5], v0 offset1:1
	v_add_u32_e32 v0, 0x8010, v10
	s_waitcnt lgkmcnt(0)
	v_cvt_pk_bf16_f32 v3, v4, v5
	ds_read2_b32 v[4:5], v0 offset1:1
	v_add_u32_e32 v0, 0x8018, v10
	s_waitcnt lgkmcnt(0)
	v_cvt_pk_bf16_f32 v4, v4, v5
	ds_read2_b32 v[8:9], v0 offset1:1
	s_waitcnt lgkmcnt(0)
	v_cvt_pk_bf16_f32 v5, v8, v9
	flat_store_dwordx4 v[6:7], v[2:5]
	v_add_u32_e32 v0, 0x8100, v10
	ds_read2_b32 v[2:3], v0 offset1:1
	v_add_u32_e32 v0, 0x8108, v10
	s_waitcnt lgkmcnt(0)
	v_cvt_pk_bf16_f32 v2, v2, v3
	ds_read2_b32 v[4:5], v0 offset1:1
	v_add_u32_e32 v0, 0x8110, v10
	s_waitcnt lgkmcnt(0)
	v_cvt_pk_bf16_f32 v3, v4, v5
	ds_read2_b32 v[4:5], v0 offset1:1
	v_add_u32_e32 v0, 0x8118, v10
	s_waitcnt lgkmcnt(0)
	v_cvt_pk_bf16_f32 v4, v4, v5
	ds_read2_b32 v[8:9], v0 offset1:1
	s_waitcnt lgkmcnt(0)
	v_cvt_pk_bf16_f32 v5, v8, v9
	flat_store_dwordx4 v[6:7], v[2:5] offset:128
	v_add_u32_e32 v0, 0x8200, v10
	ds_read2_b32 v[2:3], v0 offset1:1
	v_add_u32_e32 v0, 0x8208, v10
	s_waitcnt lgkmcnt(0)
	v_cvt_pk_bf16_f32 v2, v2, v3
	ds_read2_b32 v[4:5], v0 offset1:1
	v_add_u32_e32 v0, 0x8210, v10
	s_waitcnt lgkmcnt(0)
	v_cvt_pk_bf16_f32 v3, v4, v5
	ds_read2_b32 v[4:5], v0 offset1:1
	v_add_u32_e32 v0, 0x8218, v10
	s_waitcnt lgkmcnt(0)
	v_cvt_pk_bf16_f32 v4, v4, v5
	ds_read2_b32 v[8:9], v0 offset1:1
	s_waitcnt lgkmcnt(0)
	v_cvt_pk_bf16_f32 v5, v8, v9
	flat_store_dwordx4 v[6:7], v[2:5] offset:256
	v_add_u32_e32 v0, 0x8300, v10
	ds_read2_b32 v[2:3], v0 offset1:1
	v_add_u32_e32 v0, 0x8308, v10
	s_waitcnt lgkmcnt(0)
	v_cvt_pk_bf16_f32 v2, v2, v3
	ds_read2_b32 v[4:5], v0 offset1:1
	v_add_u32_e32 v0, 0x8310, v10
	s_waitcnt lgkmcnt(0)
	v_cvt_pk_bf16_f32 v3, v4, v5
	ds_read2_b32 v[4:5], v0 offset1:1
	v_add_u32_e32 v0, 0x8318, v10
	s_waitcnt lgkmcnt(0)
	v_cvt_pk_bf16_f32 v4, v4, v5
	ds_read2_b32 v[8:9], v0 offset1:1
	s_waitcnt lgkmcnt(0)
	v_cvt_pk_bf16_f32 v5, v8, v9
	flat_store_dwordx4 v[6:7], v[2:5] offset:384
	s_waitcnt lgkmcnt(0)
	s_barrier
	s_branch .LBB0_450

; template <int KT, class F> DEVI void cvt_tile(F colptr, int ldsrc, int k0, bf16_t* out, int ldo, int v0, float* tile, int wv) {
;     ...
;     { const int vc = tid & 63, kk = tid >> 6; const float* cp = colptr(v0 + vc) + (size_t)k0 * ldsrc; float v[8 * KT];
; #pragma unroll
;       for (int r = 0; r < 8 * KT; ++r) v[r] = cp[(size_t)(r * 8 + kk) * ldsrc];
; #pragma unroll
;       for (int r = 0; r < 8 * KT; ++r) tile[vc * PITCH + r * 8 + kk] = v[r]; }
;     __syncthreads();
; DEVI void cvt_ffn_phase(const float* wg, const float* wu, const float* wd, unsigned char* ws, char* lds, int j0, int jstride, int wv) {
;     ...
;         if (job < 352) { const int vt = job >> 2, kg = job & 3; cvt_tile<4>(ColGU{wg, (long)((const char*)wu - (const char*)wg)}, DFF, kg * 256, Wgu, DM, vt * 64, tile, wv); }
.LBB0_539:
	s_andn2_b64 vcc, exec, s[6:7]
	s_cbranch_vccnz .LBB0_536
	s_and_b32 s7, s12, 0x300
	s_and_b32 s6, s14, 0xffffffc0
	s_bitcmp1_b32 s67, 3
	s_cselect_b32 s19, s10, 0
	s_cselect_b32 s18, s11, 0
	s_add_u32 s20, s8, s19
	s_addc_u32 s21, s9, s18
	s_and_b32 s18, s16, 0xffffff80
	v_mov_b32_e32 v20, v217
	s_ashr_i32 s19, s18, 31
	s_lshl_b64 s[18:19], s[18:19], 2
	v_and_b32_e32 v21, 63, v20
	s_add_u32 s18, s20, s18
	v_and_or_b32 v0, s14, 64, v21
	s_addc_u32 s19, s21, s19
	v_lshlrev_b32_e32 v0, 2, v0
	v_ashrrev_i32_e32 v22, 6, v20
	v_lshl_add_u64 v[2:3], s[18:19], 0, v[0:1]
	s_mul_i32 s46, s7, 0x2c00
	v_lshl_add_u64 v[2:3], v[2:3], 0, s[46:47]
	v_add_u32_e32 v0, 8, v22
	v_mad_i64_i32 v[6:7], s[18:19], v0, s44, v[2:3]
	v_add_u32_e32 v0, 16, v22
	v_mad_i64_i32 v[8:9], s[18:19], v0, s44, v[2:3]
	v_add_u32_e32 v0, 24, v22
	v_mad_i64_i32 v[10:11], s[18:19], v0, s44, v[2:3]
	v_add_u32_e32 v0, 32, v22
	v_mad_i64_i32 v[12:13], s[18:19], v0, s44, v[2:3]
	v_add_u32_e32 v0, 40, v22
	v_mad_i64_i32 v[14:15], s[18:19], v0, s44, v[2:3]
	v_add_u32_e32 v0, 48, v22
	v_mad_i64_i32 v[16:17], s[18:19], v0, s44, v[2:3]
	v_add_u32_e32 v0, 56, v22
	v_mad_i64_i32 v[4:5], s[18:19], v22, s44, v[2:3]
	v_mad_i64_i32 v[18:19], s[18:19], v0, s44, v[2:3]
	global_load_dword v0, v[4:5], off nt
	global_load_dword v23, v[6:7], off nt
	global_load_dword v24, v[8:9], off
	global_load_dword v25, v[10:11], off
	global_load_dword v26, v[12:13], off
	global_load_dword v27, v[14:15], off
	global_load_dword v28, v[16:17], off
	global_load_dword v29, v[18:19], off
	v_add_u32_e32 v4, 64, v22
	v_add_u32_e32 v6, 0x48, v22
	v_add_u32_e32 v8, 0x50, v22
	v_add_u32_e32 v10, 0x58, v22
	v_add_u32_e32 v12, 0x60, v22
	v_add_u32_e32 v14, 0x68, v22
	v_add_u32_e32 v16, 0x70, v22
	v_add_u32_e32 v18, 0x78, v22
	v_mad_i64_i32 v[4:5], s[18:19], v4, s44, v[2:3]
	v_mad_i64_i32 v[6:7], s[18:19], v6, s44, v[2:3]
	v_mad_i64_i32 v[8:9], s[18:19], v8, s44, v[2:3]
	v_mad_i64_i32 v[10:11], s[18:19], v10, s44, v[2:3]
	v_mad_i64_i32 v[12:13], s[18:19], v12, s44, v[2:3]
	v_mad_i64_i32 v[14:15], s[18:19], v14, s44, v[2:3]
	v_mad_i64_i32 v[16:17], s[18:19], v16, s44, v[2:3]
	v_mad_i64_i32 v[18:19], s[18:19], v18, s44, v[2:3]
	global_load_dword v30, v[4:5], off nt
	global_load_dword v31, v[6:7], off nt
	global_load_dword v32, v[8:9], off
	global_load_dword v33, v[10:11], off
	global_load_dword v34, v[12:13], off
	global_load_dword v35, v[14:15], off
	global_load_dword v36, v[16:17], off
	global_load_dword v37, v[18:19], off
	v_add_u32_e32 v4, 0x80, v22
	v_add_u32_e32 v6, 0x88, v22
	v_add_u32_e32 v8, 0x90, v22
	v_add_u32_e32 v10, 0x98, v22
	v_add_u32_e32 v12, 0xa0, v22
	v_add_u32_e32 v14, 0xa8, v22
	v_add_u32_e32 v16, 0xb0, v22
	v_add_u32_e32 v18, 0xb8, v22
	v_mad_i64_i32 v[4:5], s[18:19], v4, s44, v[2:3]
	v_mad_i64_i32 v[6:7], s[18:19], v6, s44, v[2:3]
	v_mad_i64_i32 v[8:9], s[18:19], v8, s44, v[2:3]
	v_mad_i64_i32 v[10:11], s[18:19], v10, s44, v[2:3]
	v_mad_i64_i32 v[12:13], s[18:19], v12, s44, v[2:3]
	v_mad_i64_i32 v[14:15], s[18:19], v14, s44, v[2:3]
	v_mad_i64_i32 v[16:17], s[18:19], v16, s44, v[2:3]
	v_mad_i64_i32 v[18:19], s[18:19], v18, s44, v[2:3]
	global_load_dword v38, v[4:5], off nt
	global_load_dword v39, v[6:7], off nt
	global_load_dword v40, v[8:9], off
	global_load_dword v41, v[10:11], off
	global_load_dword v42, v[12:13], off
	global_load_dword v43, v[14:15], off
	global_load_dword v44, v[16:17], off
	s_nop 0
	global_load_dword v18, v[18:19], off
	v_add_u32_e32 v4, 0xc0, v22
	v_add_u32_e32 v6, 0xc8, v22
	v_add_u32_e32 v8, 0xd0, v22
	v_add_u32_e32 v10, 0xd8, v22
	v_add_u32_e32 v12, 0xe0, v22
	v_add_u32_e32 v14, 0xe8, v22
	v_add_u32_e32 v16, 0xf0, v22
	v_add_u32_e32 v19, 0xf8, v22
	v_mad_i64_i32 v[4:5], s[18:19], v4, s44, v[2:3]
	v_mad_i64_i32 v[6:7], s[18:19], v6, s44, v[2:3]
	v_mad_i64_i32 v[8:9], s[18:19], v8, s44, v[2:3]
	v_mad_i64_i32 v[10:11], s[18:19], v10, s44, v[2:3]
	v_mad_i64_i32 v[12:13], s[18:19], v12, s44, v[2:3]
	v_mad_i64_i32 v[14:15], s[18:19], v14, s44, v[2:3]
	v_mad_i64_i32 v[16:17], s[18:19], v16, s44, v[2:3]
	v_mad_i64_i32 v[2:3], s[18:19], v19, s44, v[2:3]
	global_load_dword v4, v[4:5], off nt
	s_nop 0
	global_load_dword v5, v[6:7], off
	s_nop 0
	global_load_dword v6, v[8:9], off
	global_load_dword v7, v[10:11], off
	s_nop 0
	global_load_dword v8, v[12:13], off
	global_load_dword v9, v[14:15], off
	global_load_dword v10, v[16:17], off
	s_nop 0
	global_load_dword v2, v[2:3], off
	v_mul_u32_u24_e32 v3, 0x404, v21
	v_lshlrev_b32_e32 v11, 2, v22
	v_add3_u32 v3, 0, v3, v11
	v_add_u32_e32 v3, 0x8000, v3
	s_waitcnt vmcnt(0)
	ds_write2_b32 v3, v0, v23 offset1:8
	ds_write2_b32 v3, v24, v25 offset0:16 offset1:24
	ds_write2_b32 v3, v26, v27 offset0:32 offset1:40
	ds_write2_b32 v3, v28, v29 offset0:48 offset1:56
	ds_write2_b32 v3, v30, v31 offset0:64 offset1:72
	ds_write2_b32 v3, v32, v33 offset0:80 offset1:88
	ds_write2_b32 v3, v34, v35 offset0:96 offset1:104
	ds_write2_b32 v3, v36, v37 offset0:112 offset1:120
	ds_write2_b32 v3, v38, v39 offset0:128 offset1:136
	ds_write2_b32 v3, v40, v41 offset0:144 offset1:152
	ds_write2_b32 v3, v42, v43 offset0:160 offset1:168
	ds_write2_b32 v3, v44, v18 offset0:176 offset1:184
	ds_write2_b32 v3, v4, v5 offset0:192 offset1:200
	ds_write2_b32 v3, v6, v7 offset0:208 offset1:216
	ds_write2_b32 v3, v8, v9 offset0:224 offset1:232
	ds_write2_b32 v3, v10, v2 offset0:240 offset1:248
	v_lshlrev_b32_e32 v2, 3, v20
	v_ashrrev_i32_e32 v0, 3, v20
	v_and_b32_e32 v10, 56, v2
	v_mul_lo_u32 v2, v0, s43
	v_lshlrev_b32_e32 v3, 2, v10
	v_add3_u32 v11, 0, v2, v3
	v_add_u32_e32 v2, 0x8000, v11
	s_waitcnt lgkmcnt(0)
	s_barrier
; DEVI unsigned cvtpk(float lo, float hi) { unsigned r; asm volatile("v_cvt_pk_bf16_f32 %0, %1, %2" : "=v"(r) : "v"(lo), "v"(hi)); return r; }
; template <int KT, class F> DEVI void cvt_tile(F colptr, int ldsrc, int k0, bf16_t* out, int ldo, int v0, float* tile, int wv) {
;     ...
;     { const int vc = tid >> 3, k8 = (tid & 7) * 8;
; #pragma unroll
;       for (int q = 0; q < KT; ++q) { const float* tp = tile + vc * PITCH + q * 64 + k8;
;         u32x4 w = {cvtpk(tp[0], tp[1]), cvtpk(tp[2], tp[3]), cvtpk(tp[4], tp[5]), cvtpk(tp[6], tp[7])};
;         *(u32x4*)(out + (size_t)(v0 + vc) * ldo + k0 + q * 64 + k8) = w; } }
;     __syncthreads();
	ds_read2_b32 v[2:3], v2 offset1:1
	s_waitcnt lgkmcnt(0)
	v_cvt_pk_bf16_f32 v2, v2, v3
	v_add_u32_e32 v3, 0x8008, v11
	ds_read2_b32 v[4:5], v3 offset1:1
	s_lshl_b32 s7, s7, 1
	v_add_u32_e32 v6, s6, v0
	s_waitcnt lgkmcnt(0)
	v_cvt_pk_bf16_f32 v3, v4, v5
	v_add_u32_e32 v4, 0x8010, v11
	s_add_u32 s18, s72, s7
	v_ashrrev_i32_e32 v7, 31, v6
	ds_read2_b32 v[4:5], v4 offset1:1
	s_addc_u32 s19, s73, 0
	v_add_u32_e32 v0, 0x8018, v11
	v_lshlrev_b64 v[6:7], 11, v[6:7]
	s_waitcnt lgkmcnt(0)
	v_cvt_pk_bf16_f32 v4, v4, v5
	ds_read2_b32 v[8:9], v0 offset1:1
	v_lshl_add_u64 v[6:7], s[18:19], 0, v[6:7]
	v_lshlrev_b32_e32 v0, 1, v10
	v_lshl_add_u64 v[6:7], v[6:7], 0, v[0:1]
	s_waitcnt lgkmcnt(0)
	v_cvt_pk_bf16_f32 v5, v8, v9
	flat_store_dwordx4 v[6:7], v[2:5]
	v_add_u32_e32 v0, 0x8100, v11
	ds_read2_b32 v[2:3], v0 offset1:1
	v_add_u32_e32 v0, 0x8108, v11
	s_waitcnt lgkmcnt(0)
	v_cvt_pk_bf16_f32 v2, v2, v3
	ds_read2_b32 v[4:5], v0 offset1:1
	v_add_u32_e32 v0, 0x8110, v11
	s_waitcnt lgkmcnt(0)
	v_cvt_pk_bf16_f32 v3, v4, v5
	ds_read2_b32 v[4:5], v0 offset1:1
	v_add_u32_e32 v0, 0x8118, v11
	s_waitcnt lgkmcnt(0)
	v_cvt_pk_bf16_f32 v4, v4, v5
	ds_read2_b32 v[8:9], v0 offset1:1
	s_waitcnt lgkmcnt(0)
	v_cvt_pk_bf16_f32 v5, v8, v9
	flat_store_dwordx4 v[6:7], v[2:5] offset:128
	v_add_u32_e32 v0, 0x8200, v11
	ds_read2_b32 v[2:3], v0 offset1:1
	v_add_u32_e32 v0, 0x8208, v11
	s_waitcnt lgkmcnt(0)
	v_cvt_pk_bf16_f32 v2, v2, v3
	ds_read2_b32 v[4:5], v0 offset1:1
	v_add_u32_e32 v0, 0x8210, v11
	s_waitcnt lgkmcnt(0)
	v_cvt_pk_bf16_f32 v3, v4, v5
	ds_read2_b32 v[4:5], v0 offset1:1
	v_add_u32_e32 v0, 0x8218, v11
	s_waitcnt lgkmcnt(0)
	v_cvt_pk_bf16_f32 v4, v4, v5
	ds_read2_b32 v[8:9], v0 offset1:1
	s_waitcnt lgkmcnt(0)
	v_cvt_pk_bf16_f32 v5, v8, v9
	flat_store_dwordx4 v[6:7], v[2:5] offset:256
	v_add_u32_e32 v0, 0x8300, v11
	ds_read2_b32 v[2:3], v0 offset1:1
	v_add_u32_e32 v0, 0x8308, v11
	s_waitcnt lgkmcnt(0)
	v_cvt_pk_bf16_f32 v2, v2, v3
	ds_read2_b32 v[4:5], v0 offset1:1
	v_add_u32_e32 v0, 0x8310, v11
	s_waitcnt lgkmcnt(0)
	v_cvt_pk_bf16_f32 v3, v4, v5
	ds_read2_b32 v[4:5], v0 offset1:1
	v_add_u32_e32 v0, 0x8318, v11
	s_waitcnt lgkmcnt(0)
	v_cvt_pk_bf16_f32 v4, v4, v5
	ds_read2_b32 v[8:9], v0 offset1:1
	s_waitcnt lgkmcnt(0)
	v_cvt_pk_bf16_f32 v5, v8, v9
	flat_store_dwordx4 v[6:7], v[2:5] offset:384
	s_waitcnt lgkmcnt(0)
	s_barrier
	s_branch .LBB0_536
